# weight-conversion streaming loops: entry wait relaxed to vmcnt(8), dead waits removed, next-unit register copies gathered behind one wait after the last store (restores load/finish overlap)
# baseline (speedup 1.0000x reference)
.LBB0_131:
	s_lshl_b32 s26, s4, 4
	s_andn2_b32 s26, s26, 63
	v_or_b32_e32 v36, s26, v66
	s_lshl_b32 s27, s4, 3
	v_lshrrev_b32_e32 v34, 1, v36
	s_and_b32 s27, s27, 0xffffff80
	v_and_b32_e32 v34, 0x70, v34
	s_lshl_b32 s4, s4, 8
	v_or3_b32 v37, s27, v34, v1
	v_mov_b32_e32 v34, s25
	v_mov_b32_e32 v35, s23
	s_or_b64 vcc, s[6:7], s[20:21]
	s_and_b32 s4, s4, 0x300
	v_cndmask_b32_e32 v35, v34, v35, vcc
	v_mov_b32_e32 v34, s24
	v_mov_b32_e32 v38, s22
	v_cndmask_b32_e64 v36, v37, v36, s[20:21]
	v_add_u32_e32 v37, s4, v67
	v_cndmask_b32_e32 v34, v34, v38, vcc
	v_ashrrev_i32_e32 v38, 31, v37
	v_mul_lo_u32 v40, s18, v38
	v_mul_lo_u32 v41, s19, v37
	v_mad_u64_u32 v[38:39], s[20:21], s18, v37, 0
	v_add3_u32 v39, v39, v40, v41
	v_lshl_add_u64 v[34:35], v[38:39], 2, v[34:35]
	v_ashrrev_i32_e32 v37, 31, v36
	v_lshl_add_u64 v[42:43], v[36:37], 2, v[34:35]
	s_lshl_b64 s[18:19], s[18:19], 8
	v_lshl_add_u64 v[50:51], v[42:43], 0, s[18:19]
	v_lshl_add_u64 v[58:59], v[50:51], 0, s[18:19]
	v_lshl_add_u64 v[62:63], v[58:59], 0, s[18:19]
	global_load_dwordx4 v[34:37], v[42:43], off offset:16
	global_load_dwordx4 v[38:41], v[42:43], off
	s_nop 0
	global_load_dwordx4 v[42:45], v[50:51], off offset:16
	global_load_dwordx4 v[46:49], v[50:51], off
	s_nop 0
	global_load_dwordx4 v[50:53], v[58:59], off offset:16
	global_load_dwordx4 v[54:57], v[58:59], off
	s_nop 0
	global_load_dwordx4 v[58:61], v[62:63], off offset:16
	s_nop 0
	global_load_dwordx4 v[62:65], v[62:63], off
	v_add_u32_e32 v72, s26, v67
	v_ashrrev_i32_e32 v73, 31, v72
	v_lshlrev_b64 v[72:73], 11, v[72:73]
	v_lshl_add_u64 v[72:73], s[16:17], 0, v[72:73]
	s_lshl_b32 s4, s4, 1
	v_lshl_add_u64 v[72:73], v[72:73], 0, s[4:5]
	v_lshl_add_u64 v[72:73], v[72:73], 0, v[68:69]
	s_branch .LBB0_132

.LBB0_132:
	s_barrier
	s_waitcnt vmcnt(8)
	ds_write2_b32 v74, v2, v3 offset1:1
	ds_write2_b32 v74, v4, v5 offset0:2 offset1:3
	s_nop 0
	ds_write2_b32 v74, v6, v7 offset0:4 offset1:5
	ds_write2_b32 v74, v8, v9 offset0:6 offset1:7
	v_add_u32_e32 v2, 0x4100, v74
	s_nop 0
	ds_write2_b32 v2, v10, v11 offset1:1
	v_add_u32_e32 v2, 0x4108, v74
	ds_write2_b32 v2, v12, v13 offset1:1
	v_add_u32_e32 v2, 0x4110, v74
	s_nop 0
	ds_write2_b32 v2, v14, v15 offset1:1
	v_add_u32_e32 v2, 0x4118, v74
	ds_write2_b32 v2, v16, v17 offset1:1
	v_add_u32_e32 v2, 0x8200, v74
	s_nop 0
	ds_write2_b32 v2, v18, v19 offset1:1
	v_add_u32_e32 v2, 0x8208, v74
	ds_write2_b32 v2, v20, v21 offset1:1
	v_add_u32_e32 v2, 0x8210, v74
	s_nop 0
	ds_write2_b32 v2, v22, v23 offset1:1
	v_add_u32_e32 v2, 0x8218, v74
	ds_write2_b32 v2, v24, v25 offset1:1
	v_add_u32_e32 v2, 0xc300, v74
	s_nop 0
	ds_write2_b32 v2, v26, v27 offset1:1
	v_add_u32_e32 v2, 0xc308, v74
	ds_write2_b32 v2, v28, v29 offset1:1
	v_add_u32_e32 v2, 0xc310, v74
	s_nop 0
	ds_write2_b32 v2, v30, v31 offset1:1
	v_add_u32_e32 v2, 0xc318, v74
	ds_write2_b32 v2, v32, v33 offset1:1
	s_waitcnt lgkmcnt(0)
	s_barrier
	ds_read2_b32 v[2:3], v75 offset1:65
	ds_read2_b32 v[4:5], v75 offset0:130 offset1:195
	v_add_u32_e32 v8, 0x400, v75
	ds_read2_b32 v[6:7], v8 offset0:4 offset1:69
	ds_read2_b32 v[8:9], v8 offset0:134 offset1:199
	v_add_u32_e32 v10, 0x4400, v75
	s_waitcnt lgkmcnt(3)
	v_cvt_pk_bf16_f32 v2, v2, v3
	s_waitcnt lgkmcnt(2)
	v_cvt_pk_bf16_f32 v3, v4, v5
	s_waitcnt lgkmcnt(1)
	v_cvt_pk_bf16_f32 v4, v6, v7
	v_add_u32_e32 v6, 0x4000, v75
	v_add_u32_e32 v12, 0x4600, v75
	s_waitcnt lgkmcnt(0)
	v_cvt_pk_bf16_f32 v5, v8, v9
	ds_read2_b32 v[6:7], v6 offset0:64 offset1:129
	v_add_u32_e32 v8, 0x4200, v75
	ds_read2_b32 v[10:11], v10 offset0:68 offset1:133
	ds_read2_b32 v[12:13], v12 offset0:70 offset1:135
	ds_read2_b32 v[8:9], v8 offset0:66 offset1:131
	global_store_dwordx4 v[70:71], v[2:5], off
	s_andn2_b64 vcc, exec, s[14:15]
	s_nop 0
	s_waitcnt lgkmcnt(3)
	v_cvt_pk_bf16_f32 v2, v6, v7
	s_waitcnt lgkmcnt(2)
	v_cvt_pk_bf16_f32 v4, v10, v11
	s_waitcnt lgkmcnt(1)
	v_cvt_pk_bf16_f32 v5, v12, v13
	v_add_u32_e32 v6, 0x8000, v75
	v_add_u32_e32 v10, 0x8400, v75
	v_add_u32_e32 v12, 0x8800, v75
	s_waitcnt lgkmcnt(0)
	v_cvt_pk_bf16_f32 v3, v8, v9
	ds_read2_b32 v[6:7], v6 offset0:128 offset1:193
	ds_read2_b32 v[8:9], v10 offset0:2 offset1:67
	ds_read2_b32 v[10:11], v10 offset0:132 offset1:197
	ds_read2_b32 v[12:13], v12 offset0:6 offset1:71
	global_store_dwordx4 v[70:71], v[2:5], off offset:128
	s_nop 0
	s_nop 0
	s_waitcnt lgkmcnt(3)
	v_cvt_pk_bf16_f32 v2, v6, v7
	s_waitcnt lgkmcnt(2)
	v_cvt_pk_bf16_f32 v3, v8, v9
	s_waitcnt lgkmcnt(1)
	v_cvt_pk_bf16_f32 v4, v10, v11
	s_waitcnt lgkmcnt(0)
	v_cvt_pk_bf16_f32 v5, v12, v13
	v_add_u32_e32 v6, 0xc200, v75
	v_add_u32_e32 v8, 0xc400, v75
	v_add_u32_e32 v10, 0xc600, v75
	v_add_u32_e32 v12, 0xc800, v75
	ds_read2_b32 v[6:7], v6 offset0:64 offset1:129
	ds_read2_b32 v[8:9], v8 offset0:66 offset1:131
	ds_read2_b32 v[10:11], v10 offset0:68 offset1:133
	ds_read2_b32 v[12:13], v12 offset0:70 offset1:135
	global_store_dwordx4 v[70:71], v[2:5], off offset:256
	s_nop 0
	s_nop 0
	s_waitcnt lgkmcnt(3)
	v_cvt_pk_bf16_f32 v2, v6, v7
	s_waitcnt lgkmcnt(2)
	v_cvt_pk_bf16_f32 v3, v8, v9
	s_waitcnt lgkmcnt(1)
	v_cvt_pk_bf16_f32 v4, v10, v11
	s_waitcnt lgkmcnt(0)
	v_cvt_pk_bf16_f32 v5, v12, v13
	global_store_dwordx4 v[70:71], v[2:5], off offset:384
	s_waitcnt vmcnt(0)
	v_mov_b32_e32 v14, v42
	v_mov_b32_e32 v15, v43
	v_mov_b32_e32 v16, v44
	v_mov_b32_e32 v17, v45
	v_mov_b32_e32 v18, v54
	v_mov_b64_e32 v[70:71], v[72:73]
	v_mov_b32_e32 v6, v34
	v_mov_b32_e32 v2, v38
	v_mov_b32_e32 v3, v39
	v_mov_b32_e32 v4, v40
	v_mov_b32_e32 v5, v41
	v_mov_b32_e32 v7, v35
	v_mov_b32_e32 v8, v36
	v_mov_b32_e32 v9, v37
	v_mov_b32_e32 v10, v46
	v_mov_b32_e32 v11, v47
	v_mov_b32_e32 v12, v48
	v_mov_b32_e32 v13, v49
	v_mov_b32_e32 v19, v55
	v_mov_b32_e32 v20, v56
	v_mov_b32_e32 v21, v57
	v_mov_b32_e32 v22, v50
	v_mov_b32_e32 v23, v51
	v_mov_b32_e32 v24, v52
	v_mov_b32_e32 v25, v53
	v_mov_b32_e32 v26, v62
	v_mov_b32_e32 v27, v63
	v_mov_b32_e32 v28, v64
	v_mov_b32_e32 v29, v65
	v_mov_b32_e32 v30, v58
	v_mov_b32_e32 v31, v59
	v_mov_b32_e32 v32, v60
	v_mov_b32_e32 v33, v61
	s_cbranch_vccz .LBB0_147

.LBB0_287:
	s_lshl_b32 s18, s73, 4
	s_and_b32 s18, s18, 0x7c0
	v_or_b32_e32 v36, s18, v66
	s_lshl_b32 s60, s73, 3
	v_lshrrev_b32_e32 v34, 1, v36
	s_and_b32 s60, s60, 0x380
	v_and_b32_e32 v34, 0x70, v34
	v_or3_b32 v37, s60, v34, v67
	v_mov_b32_e32 v34, s57
	v_mov_b32_e32 v35, s59
	s_or_b64 vcc, s[0:1], s[6:7]
	v_cndmask_b32_e32 v35, v34, v35, vcc
	v_mov_b32_e32 v34, s56
	v_mov_b32_e32 v38, s58
	v_cndmask_b32_e32 v34, v34, v38, vcc
	v_cndmask_b32_e64 v38, v37, v36, s[6:7]
	s_lshl_b32 s6, s73, 8
	s_and_b32 s6, s6, 0x300
	v_add_u32_e32 v36, s6, v68
	v_ashrrev_i32_e32 v37, 31, v36
	v_lshlrev_b64 v[36:37], 12, v[36:37]
	v_lshl_add_u64 v[34:35], v[34:35], 0, v[36:37]
	v_lshlrev_b32_e32 v98, 2, v38
	v_lshl_add_u64 v[58:59], v[34:35], 0, v[98:99]
	v_add_co_u32_e32 v42, vcc, s37, v58
	global_load_dwordx4 v[34:37], v[58:59], off offset:16
	global_load_dwordx4 v[38:41], v[58:59], off
	v_addc_co_u32_e32 v43, vcc, 0, v59, vcc
	v_add_co_u32_e32 v50, vcc, s65, v58
	v_lshl_add_u64 v[46:47], v[58:59], 0, s[68:69]
	s_nop 0
	v_addc_co_u32_e32 v51, vcc, 0, v59, vcc
	v_lshl_add_u64 v[54:55], v[58:59], 0, s[30:31]
	v_lshl_add_u64 v[62:63], v[58:59], 0, s[24:25]
	v_add_co_u32_e32 v58, vcc, 0xc0000, v58
	global_load_dwordx4 v[42:45], v[42:43], off
	s_nop 0
	global_load_dwordx4 v[46:49], v[46:47], off offset:16
	v_addc_co_u32_e32 v59, vcc, 0, v59, vcc
	global_load_dwordx4 v[50:53], v[50:51], off
	s_nop 0
	global_load_dwordx4 v[54:57], v[54:55], off offset:16
	s_nop 0
	global_load_dwordx4 v[58:61], v[58:59], off
	s_nop 0
	global_load_dwordx4 v[62:65], v[62:63], off offset:16
	v_add_u32_e32 v74, s18, v68
	v_ashrrev_i32_e32 v75, 31, v74
	v_lshlrev_b64 v[74:75], 11, v[74:75]
	v_lshl_add_u64 v[74:75], s[38:39], 0, v[74:75]
	s_lshl_b32 s66, s6, 1
	v_lshl_add_u64 v[74:75], v[74:75], 0, s[66:67]
	v_mov_b32_e32 v71, v99
	v_lshl_add_u64 v[74:75], v[74:75], 0, v[70:71]
	s_branch .LBB0_288

.LBB0_288:
	s_barrier
	s_waitcnt vmcnt(8)
	ds_write2_b32 v69, v2, v3 offset1:1
	ds_write2_b32 v69, v4, v5 offset0:2 offset1:3
	s_nop 0
	ds_write2_b32 v69, v6, v7 offset0:4 offset1:5
	ds_write2_b32 v69, v8, v9 offset0:6 offset1:7
	v_add_u32_e32 v2, 0x4100, v69
	s_nop 0
	ds_write2_b32 v2, v10, v11 offset1:1
	v_add_u32_e32 v2, 0x4108, v69
	ds_write2_b32 v2, v12, v13 offset1:1
	v_add_u32_e32 v2, 0x4110, v69
	s_nop 0
	ds_write2_b32 v2, v14, v15 offset1:1
	v_add_u32_e32 v2, 0x4118, v69
	ds_write2_b32 v2, v16, v17 offset1:1
	v_add_u32_e32 v2, 0x8200, v69
	s_nop 0
	ds_write2_b32 v2, v18, v19 offset1:1
	v_add_u32_e32 v2, 0x8208, v69
	ds_write2_b32 v2, v20, v21 offset1:1
	v_add_u32_e32 v2, 0x8210, v69
	s_nop 0
	ds_write2_b32 v2, v22, v23 offset1:1
	v_add_u32_e32 v2, 0x8218, v69
	ds_write2_b32 v2, v24, v25 offset1:1
	v_add_u32_e32 v2, 0xc300, v69
	s_nop 0
	ds_write2_b32 v2, v26, v27 offset1:1
	v_add_u32_e32 v2, 0xc308, v69
	ds_write2_b32 v2, v28, v29 offset1:1
	v_add_u32_e32 v2, 0xc310, v69
	s_nop 0
	ds_write2_b32 v2, v30, v31 offset1:1
	v_add_u32_e32 v2, 0xc318, v69
	ds_write2_b32 v2, v32, v33 offset1:1
	s_waitcnt lgkmcnt(0)
	s_barrier
	ds_read2_b32 v[2:3], v76 offset1:65
	ds_read2_b32 v[4:5], v76 offset0:130 offset1:195
	v_add_u32_e32 v8, 0x400, v76
	ds_read2_b32 v[6:7], v8 offset0:4 offset1:69
	ds_read2_b32 v[8:9], v8 offset0:134 offset1:199
	v_add_u32_e32 v10, 0x4400, v76
	s_waitcnt lgkmcnt(3)
	v_cvt_pk_bf16_f32 v2, v2, v3
	s_waitcnt lgkmcnt(2)
	v_cvt_pk_bf16_f32 v3, v4, v5
	s_waitcnt lgkmcnt(1)
	v_cvt_pk_bf16_f32 v4, v6, v7
	v_add_u32_e32 v6, 0x4000, v76
	v_add_u32_e32 v12, 0x4600, v76
	s_waitcnt lgkmcnt(0)
	v_cvt_pk_bf16_f32 v5, v8, v9
	ds_read2_b32 v[6:7], v6 offset0:64 offset1:129
	v_add_u32_e32 v8, 0x4200, v76
	ds_read2_b32 v[10:11], v10 offset0:68 offset1:133
	ds_read2_b32 v[12:13], v12 offset0:70 offset1:135
	ds_read2_b32 v[8:9], v8 offset0:66 offset1:131
	global_store_dwordx4 v[72:73], v[2:5], off
	s_add_i32 s64, s64, 1
	s_cmp_ge_u32 s72, s33
	s_waitcnt lgkmcnt(3)
	v_cvt_pk_bf16_f32 v2, v6, v7
	s_waitcnt lgkmcnt(2)
	v_cvt_pk_bf16_f32 v4, v10, v11
	s_waitcnt lgkmcnt(1)
	v_cvt_pk_bf16_f32 v5, v12, v13
	v_add_u32_e32 v6, 0x8000, v76
	v_add_u32_e32 v10, 0x8400, v76
	v_add_u32_e32 v12, 0x8800, v76
	s_waitcnt lgkmcnt(0)
	v_cvt_pk_bf16_f32 v3, v8, v9
	ds_read2_b32 v[6:7], v6 offset0:128 offset1:193
	ds_read2_b32 v[8:9], v10 offset0:2 offset1:67
	ds_read2_b32 v[10:11], v10 offset0:132 offset1:197
	ds_read2_b32 v[12:13], v12 offset0:6 offset1:71
	global_store_dwordx4 v[72:73], v[2:5], off offset:128
	s_nop 0
	s_nop 0
	s_waitcnt lgkmcnt(3)
	v_cvt_pk_bf16_f32 v2, v6, v7
	s_waitcnt lgkmcnt(2)
	v_cvt_pk_bf16_f32 v3, v8, v9
	s_waitcnt lgkmcnt(1)
	v_cvt_pk_bf16_f32 v4, v10, v11
	s_waitcnt lgkmcnt(0)
	v_cvt_pk_bf16_f32 v5, v12, v13
	v_add_u32_e32 v6, 0xc200, v76
	v_add_u32_e32 v8, 0xc400, v76
	v_add_u32_e32 v10, 0xc600, v76
	v_add_u32_e32 v12, 0xc800, v76
	ds_read2_b32 v[6:7], v6 offset0:64 offset1:129
	ds_read2_b32 v[8:9], v8 offset0:66 offset1:131
	ds_read2_b32 v[10:11], v10 offset0:68 offset1:133
	ds_read2_b32 v[12:13], v12 offset0:70 offset1:135
	global_store_dwordx4 v[72:73], v[2:5], off offset:256
	s_nop 0
	s_nop 0
	s_waitcnt lgkmcnt(3)
	v_cvt_pk_bf16_f32 v2, v6, v7
	s_waitcnt lgkmcnt(2)
	v_cvt_pk_bf16_f32 v3, v8, v9
	s_waitcnt lgkmcnt(1)
	v_cvt_pk_bf16_f32 v4, v10, v11
	s_waitcnt lgkmcnt(0)
	v_cvt_pk_bf16_f32 v5, v12, v13
	global_store_dwordx4 v[72:73], v[2:5], off offset:384
	s_waitcnt vmcnt(0)
	v_mov_b32_e32 v14, v46
	v_mov_b32_e32 v15, v47
	v_mov_b32_e32 v16, v48
	v_mov_b32_e32 v17, v49
	v_mov_b64_e32 v[72:73], v[74:75]
	v_mov_b32_e32 v6, v34
	v_mov_b32_e32 v2, v38
	v_mov_b32_e32 v3, v39
	v_mov_b32_e32 v4, v40
	v_mov_b32_e32 v5, v41
	v_mov_b32_e32 v7, v35
	v_mov_b32_e32 v8, v36
	v_mov_b32_e32 v9, v37
	v_mov_b32_e32 v10, v42
	v_mov_b32_e32 v11, v43
	v_mov_b32_e32 v12, v44
	v_mov_b32_e32 v13, v45
	v_mov_b32_e32 v18, v50
	v_mov_b32_e32 v19, v51
	v_mov_b32_e32 v20, v52
	v_mov_b32_e32 v21, v53
	v_mov_b32_e32 v22, v54
	v_mov_b32_e32 v23, v55
	v_mov_b32_e32 v24, v56
	v_mov_b32_e32 v25, v57
	v_mov_b32_e32 v26, v58
	v_mov_b32_e32 v27, v59
	v_mov_b32_e32 v28, v60
	v_mov_b32_e32 v29, v61
	v_mov_b32_e32 v30, v62
	v_mov_b32_e32 v31, v63
	v_mov_b32_e32 v32, v64
	v_mov_b32_e32 v33, v65
	s_cbranch_scc1 .LBB0_294

.LBB0_704:
	s_lshl_b32 s4, s26, 4
	s_andn2_b32 s4, s4, 63
	v_or_b32_e32 v36, s4, v66
	s_lshl_b32 s22, s26, 3
	v_lshrrev_b32_e32 v34, 1, v36
	s_and_b32 s22, s22, 0xffffff80
	v_and_b32_e32 v34, 0x70, v34
	v_or3_b32 v37, s22, v34, v1
	v_mov_b32_e32 v34, s17
	v_mov_b32_e32 v35, s15
	s_or_b64 vcc, s[0:1], s[18:19]
	v_mov_b32_e32 v38, s14
	s_lshl_b32 s14, s26, 8
	v_cndmask_b32_e32 v35, v34, v35, vcc
	v_mov_b32_e32 v34, s16
	s_and_b32 s16, s14, 0x300
	v_cndmask_b32_e64 v36, v37, v36, s[18:19]
	v_add_u32_e32 v37, s16, v67
	v_cndmask_b32_e32 v34, v34, v38, vcc
	v_ashrrev_i32_e32 v38, 31, v37
	v_mul_lo_u32 v40, s20, v38
	v_mul_lo_u32 v41, s21, v37
	v_mad_u64_u32 v[38:39], s[14:15], s20, v37, 0
	v_add3_u32 v39, v39, v40, v41
	v_lshl_add_u64 v[34:35], v[38:39], 2, v[34:35]
	v_ashrrev_i32_e32 v37, 31, v36
	v_lshl_add_u64 v[42:43], v[36:37], 2, v[34:35]
	s_lshl_b64 s[14:15], s[20:21], 8
	v_lshl_add_u64 v[50:51], v[42:43], 0, s[14:15]
	v_lshl_add_u64 v[58:59], v[50:51], 0, s[14:15]
	v_lshl_add_u64 v[62:63], v[58:59], 0, s[14:15]
	global_load_dwordx4 v[34:37], v[42:43], off offset:16
	global_load_dwordx4 v[38:41], v[42:43], off
	s_nop 0
	global_load_dwordx4 v[42:45], v[50:51], off offset:16
	global_load_dwordx4 v[46:49], v[50:51], off
	s_nop 0
	global_load_dwordx4 v[50:53], v[58:59], off offset:16
	global_load_dwordx4 v[54:57], v[58:59], off
	s_nop 0
	global_load_dwordx4 v[58:61], v[62:63], off offset:16
	s_nop 0
	global_load_dwordx4 v[62:65], v[62:63], off
	v_add_u32_e32 v72, s4, v67
	v_ashrrev_i32_e32 v73, 31, v72
	v_lshlrev_b64 v[72:73], 11, v[72:73]
	v_lshl_add_u64 v[72:73], s[12:13], 0, v[72:73]
	s_lshl_b32 s4, s16, 1
	v_lshl_add_u64 v[72:73], v[72:73], 0, s[4:5]
	v_lshlrev_b32_e32 v68, 1, v66
	v_lshl_add_u64 v[72:73], v[72:73], 0, v[68:69]
	s_branch .LBB0_705

.LBB0_705:
	s_barrier
	s_waitcnt vmcnt(8)
	ds_write2_b32 v74, v2, v3 offset1:1
	ds_write2_b32 v74, v4, v5 offset0:2 offset1:3
	s_nop 0
	ds_write2_b32 v74, v6, v7 offset0:4 offset1:5
	ds_write2_b32 v74, v8, v9 offset0:6 offset1:7
	v_add_u32_e32 v2, 0x4100, v74
	s_nop 0
	ds_write2_b32 v2, v10, v11 offset1:1
	v_add_u32_e32 v2, 0x4108, v74
	ds_write2_b32 v2, v12, v13 offset1:1
	v_add_u32_e32 v2, 0x4110, v74
	s_nop 0
	ds_write2_b32 v2, v14, v15 offset1:1
	v_add_u32_e32 v2, 0x4118, v74
	ds_write2_b32 v2, v16, v17 offset1:1
	v_add_u32_e32 v2, 0x8200, v74
	s_nop 0
	ds_write2_b32 v2, v18, v19 offset1:1
	v_add_u32_e32 v2, 0x8208, v74
	ds_write2_b32 v2, v20, v21 offset1:1
	v_add_u32_e32 v2, 0x8210, v74
	s_nop 0
	ds_write2_b32 v2, v22, v23 offset1:1
	v_add_u32_e32 v2, 0x8218, v74
	ds_write2_b32 v2, v24, v25 offset1:1
	v_add_u32_e32 v2, 0xc300, v74
	s_nop 0
	ds_write2_b32 v2, v26, v27 offset1:1
	v_add_u32_e32 v2, 0xc308, v74
	ds_write2_b32 v2, v28, v29 offset1:1
	v_add_u32_e32 v2, 0xc310, v74
	s_nop 0
	ds_write2_b32 v2, v30, v31 offset1:1
	v_add_u32_e32 v2, 0xc318, v74
	ds_write2_b32 v2, v32, v33 offset1:1
	s_waitcnt lgkmcnt(0)
	s_barrier
	ds_read2_b32 v[2:3], v75 offset1:65
	ds_read2_b32 v[4:5], v75 offset0:130 offset1:195
	v_add_u32_e32 v8, 0x400, v75
	ds_read2_b32 v[6:7], v8 offset0:4 offset1:69
	ds_read2_b32 v[8:9], v8 offset0:134 offset1:199
	v_add_u32_e32 v10, 0x4400, v75
	s_waitcnt lgkmcnt(3)
	v_cvt_pk_bf16_f32 v2, v2, v3
	s_waitcnt lgkmcnt(2)
	v_cvt_pk_bf16_f32 v3, v4, v5
	s_waitcnt lgkmcnt(1)
	v_cvt_pk_bf16_f32 v4, v6, v7
	v_add_u32_e32 v6, 0x4000, v75
	v_add_u32_e32 v12, 0x4600, v75
	s_waitcnt lgkmcnt(0)
	v_cvt_pk_bf16_f32 v5, v8, v9
	ds_read2_b32 v[6:7], v6 offset0:64 offset1:129
	v_add_u32_e32 v8, 0x4200, v75
	ds_read2_b32 v[10:11], v10 offset0:68 offset1:133
	ds_read2_b32 v[12:13], v12 offset0:70 offset1:135
	ds_read2_b32 v[8:9], v8 offset0:66 offset1:131
	global_store_dwordx4 v[70:71], v[2:5], off
	s_cmpk_lt_i32 s25, 0x13d0
	s_mov_b32 s12, s25
	s_waitcnt lgkmcnt(3)
	v_cvt_pk_bf16_f32 v2, v6, v7
	s_waitcnt lgkmcnt(2)
	v_cvt_pk_bf16_f32 v4, v10, v11
	s_waitcnt lgkmcnt(1)
	v_cvt_pk_bf16_f32 v5, v12, v13
	v_add_u32_e32 v6, 0x8000, v75
	v_add_u32_e32 v10, 0x8400, v75
	v_add_u32_e32 v12, 0x8800, v75
	s_waitcnt lgkmcnt(0)
	v_cvt_pk_bf16_f32 v3, v8, v9
	ds_read2_b32 v[6:7], v6 offset0:128 offset1:193
	ds_read2_b32 v[8:9], v10 offset0:2 offset1:67
	ds_read2_b32 v[10:11], v10 offset0:132 offset1:197
	ds_read2_b32 v[12:13], v12 offset0:6 offset1:71
	global_store_dwordx4 v[70:71], v[2:5], off offset:128
	s_nop 0
	s_nop 0
	s_waitcnt lgkmcnt(3)
	v_cvt_pk_bf16_f32 v2, v6, v7
	s_waitcnt lgkmcnt(2)
	v_cvt_pk_bf16_f32 v3, v8, v9
	s_waitcnt lgkmcnt(1)
	v_cvt_pk_bf16_f32 v4, v10, v11
	s_waitcnt lgkmcnt(0)
	v_cvt_pk_bf16_f32 v5, v12, v13
	v_add_u32_e32 v6, 0xc200, v75
	v_add_u32_e32 v8, 0xc400, v75
	v_add_u32_e32 v10, 0xc600, v75
	v_add_u32_e32 v12, 0xc800, v75
	ds_read2_b32 v[6:7], v6 offset0:64 offset1:129
	ds_read2_b32 v[8:9], v8 offset0:66 offset1:131
	ds_read2_b32 v[10:11], v10 offset0:68 offset1:133
	ds_read2_b32 v[12:13], v12 offset0:70 offset1:135
	global_store_dwordx4 v[70:71], v[2:5], off offset:256
	s_nop 0
	s_nop 0
	s_waitcnt lgkmcnt(3)
	v_cvt_pk_bf16_f32 v2, v6, v7
	s_waitcnt lgkmcnt(2)
	v_cvt_pk_bf16_f32 v3, v8, v9
	s_waitcnt lgkmcnt(1)
	v_cvt_pk_bf16_f32 v4, v10, v11
	s_waitcnt lgkmcnt(0)
	v_cvt_pk_bf16_f32 v5, v12, v13
	global_store_dwordx4 v[70:71], v[2:5], off offset:384
	s_waitcnt vmcnt(0)
	v_mov_b32_e32 v14, v42
	v_mov_b32_e32 v15, v43
	v_mov_b32_e32 v16, v44
	v_mov_b32_e32 v17, v45
	v_mov_b64_e32 v[70:71], v[72:73]
	v_mov_b32_e32 v6, v34
	v_mov_b32_e32 v2, v38
	v_mov_b32_e32 v3, v39
	v_mov_b32_e32 v4, v40
	v_mov_b32_e32 v5, v41
	v_mov_b32_e32 v7, v35
	v_mov_b32_e32 v8, v36
	v_mov_b32_e32 v9, v37
	v_mov_b32_e32 v10, v46
	v_mov_b32_e32 v11, v47
	v_mov_b32_e32 v12, v48
	v_mov_b32_e32 v13, v49
	v_mov_b32_e32 v18, v54
	v_mov_b32_e32 v19, v55
	v_mov_b32_e32 v20, v56
	v_mov_b32_e32 v21, v57
	v_mov_b32_e32 v22, v50
	v_mov_b32_e32 v23, v51
	v_mov_b32_e32 v24, v52
	v_mov_b32_e32 v25, v53
	v_mov_b32_e32 v26, v62
	v_mov_b32_e32 v27, v63
	v_mov_b32_e32 v28, v64
	v_mov_b32_e32 v29, v65
	v_mov_b32_e32 v30, v58
	v_mov_b32_e32 v31, v59
	v_mov_b32_e32 v32, v60
	v_mov_b32_e32 v33, v61
	s_cbranch_scc0 .LBB0_728

.LBB0_1301:
	s_lshl_b32 s2, s24, 4
	s_andn2_b32 s2, s2, 63
	v_or_b32_e32 v36, s2, v66
	s_lshl_b32 s20, s24, 3
	v_lshrrev_b32_e32 v34, 1, v36
	s_and_b32 s20, s20, 0xffffff80
	v_and_b32_e32 v34, 0x70, v34
	v_or3_b32 v37, s20, v34, v1
	v_mov_b32_e32 v34, s15
	v_mov_b32_e32 v35, s13
	s_or_b64 vcc, s[0:1], s[16:17]
	v_mov_b32_e32 v38, s12
	s_lshl_b32 s12, s24, 8
	v_cndmask_b32_e32 v35, v34, v35, vcc
	v_mov_b32_e32 v34, s14
	s_and_b32 s14, s12, 0x300
	v_cndmask_b32_e64 v36, v37, v36, s[16:17]
	v_add_u32_e32 v37, s14, v67
	v_cndmask_b32_e32 v34, v34, v38, vcc
	v_ashrrev_i32_e32 v38, 31, v37
	v_mul_lo_u32 v40, s18, v38
	v_mul_lo_u32 v41, s19, v37
	v_mad_u64_u32 v[38:39], s[12:13], s18, v37, 0
	v_add3_u32 v39, v39, v40, v41
	v_lshl_add_u64 v[34:35], v[38:39], 2, v[34:35]
	v_ashrrev_i32_e32 v37, 31, v36
	v_lshl_add_u64 v[42:43], v[36:37], 2, v[34:35]
	s_lshl_b64 s[12:13], s[18:19], 8
	v_lshl_add_u64 v[50:51], v[42:43], 0, s[12:13]
	v_lshl_add_u64 v[58:59], v[50:51], 0, s[12:13]
	v_lshl_add_u64 v[62:63], v[58:59], 0, s[12:13]
	global_load_dwordx4 v[34:37], v[42:43], off offset:16
	global_load_dwordx4 v[38:41], v[42:43], off
	s_nop 0
	global_load_dwordx4 v[42:45], v[50:51], off offset:16
	global_load_dwordx4 v[46:49], v[50:51], off
	s_nop 0
	global_load_dwordx4 v[50:53], v[58:59], off offset:16
	global_load_dwordx4 v[54:57], v[58:59], off
	s_nop 0
	global_load_dwordx4 v[58:61], v[62:63], off offset:16
	s_nop 0
	global_load_dwordx4 v[62:65], v[62:63], off
	v_add_u32_e32 v72, s2, v67
	v_ashrrev_i32_e32 v73, 31, v72
	v_lshlrev_b64 v[72:73], 11, v[72:73]
	v_lshl_add_u64 v[72:73], s[10:11], 0, v[72:73]
	s_lshl_b32 s2, s14, 1
	v_lshl_add_u64 v[72:73], v[72:73], 0, s[2:3]
	v_lshl_add_u64 v[72:73], v[72:73], 0, v[68:69]
	s_branch .LBB0_1302

.LBB0_1302:
	s_barrier
	s_waitcnt vmcnt(8)
	ds_write2_b32 v74, v2, v3 offset1:1
	ds_write2_b32 v74, v4, v5 offset0:2 offset1:3
	s_nop 0
	ds_write2_b32 v74, v6, v7 offset0:4 offset1:5
	ds_write2_b32 v74, v8, v9 offset0:6 offset1:7
	v_add_u32_e32 v2, 0x4100, v74
	s_nop 0
	ds_write2_b32 v2, v10, v11 offset1:1
	v_add_u32_e32 v2, 0x4108, v74
	ds_write2_b32 v2, v12, v13 offset1:1
	v_add_u32_e32 v2, 0x4110, v74
	s_nop 0
	ds_write2_b32 v2, v14, v15 offset1:1
	v_add_u32_e32 v2, 0x4118, v74
	ds_write2_b32 v2, v16, v17 offset1:1
	v_add_u32_e32 v2, 0x8200, v74
	s_nop 0
	ds_write2_b32 v2, v18, v19 offset1:1
	v_add_u32_e32 v2, 0x8208, v74
	ds_write2_b32 v2, v20, v21 offset1:1
	v_add_u32_e32 v2, 0x8210, v74
	s_nop 0
	ds_write2_b32 v2, v22, v23 offset1:1
	v_add_u32_e32 v2, 0x8218, v74
	ds_write2_b32 v2, v24, v25 offset1:1
	v_add_u32_e32 v2, 0xc300, v74
	s_nop 0
	ds_write2_b32 v2, v26, v27 offset1:1
	v_add_u32_e32 v2, 0xc308, v74
	ds_write2_b32 v2, v28, v29 offset1:1
	v_add_u32_e32 v2, 0xc310, v74
	s_nop 0
	ds_write2_b32 v2, v30, v31 offset1:1
	v_add_u32_e32 v2, 0xc318, v74
	ds_write2_b32 v2, v32, v33 offset1:1
	s_waitcnt lgkmcnt(0)
	s_barrier
	ds_read2_b32 v[2:3], v75 offset1:65
	ds_read2_b32 v[4:5], v75 offset0:130 offset1:195
	v_add_u32_e32 v8, 0x400, v75
	ds_read2_b32 v[6:7], v8 offset0:4 offset1:69
	ds_read2_b32 v[8:9], v8 offset0:134 offset1:199
	v_add_u32_e32 v10, 0x4400, v75
	s_waitcnt lgkmcnt(3)
	v_cvt_pk_bf16_f32 v2, v2, v3
	s_waitcnt lgkmcnt(2)
	v_cvt_pk_bf16_f32 v3, v4, v5
	s_waitcnt lgkmcnt(1)
	v_cvt_pk_bf16_f32 v4, v6, v7
	v_add_u32_e32 v6, 0x4000, v75
	v_add_u32_e32 v12, 0x4600, v75
	s_waitcnt lgkmcnt(0)
	v_cvt_pk_bf16_f32 v5, v8, v9
	ds_read2_b32 v[6:7], v6 offset0:64 offset1:129
	v_add_u32_e32 v8, 0x4200, v75
	ds_read2_b32 v[10:11], v10 offset0:68 offset1:133
	ds_read2_b32 v[12:13], v12 offset0:70 offset1:135
	ds_read2_b32 v[8:9], v8 offset0:66 offset1:131
	global_store_dwordx4 v[70:71], v[2:5], off
	s_cmpk_lt_i32 s23, 0x19d0
	s_mov_b32 s10, s23
	s_waitcnt lgkmcnt(3)
	v_cvt_pk_bf16_f32 v2, v6, v7
	s_waitcnt lgkmcnt(2)
	v_cvt_pk_bf16_f32 v4, v10, v11
	s_waitcnt lgkmcnt(1)
	v_cvt_pk_bf16_f32 v5, v12, v13
	v_add_u32_e32 v6, 0x8000, v75
	v_add_u32_e32 v10, 0x8400, v75
	v_add_u32_e32 v12, 0x8800, v75
	s_waitcnt lgkmcnt(0)
	v_cvt_pk_bf16_f32 v3, v8, v9
	ds_read2_b32 v[6:7], v6 offset0:128 offset1:193
	ds_read2_b32 v[8:9], v10 offset0:2 offset1:67
	ds_read2_b32 v[10:11], v10 offset0:132 offset1:197
	ds_read2_b32 v[12:13], v12 offset0:6 offset1:71
	global_store_dwordx4 v[70:71], v[2:5], off offset:128
	s_nop 0
	s_nop 0
	s_waitcnt lgkmcnt(3)
	v_cvt_pk_bf16_f32 v2, v6, v7
	s_waitcnt lgkmcnt(2)
	v_cvt_pk_bf16_f32 v3, v8, v9
	s_waitcnt lgkmcnt(1)
	v_cvt_pk_bf16_f32 v4, v10, v11
	s_waitcnt lgkmcnt(0)
	v_cvt_pk_bf16_f32 v5, v12, v13
	v_add_u32_e32 v6, 0xc200, v75
	v_add_u32_e32 v8, 0xc400, v75
	v_add_u32_e32 v10, 0xc600, v75
	v_add_u32_e32 v12, 0xc800, v75
	ds_read2_b32 v[6:7], v6 offset0:64 offset1:129
	ds_read2_b32 v[8:9], v8 offset0:66 offset1:131
	ds_read2_b32 v[10:11], v10 offset0:68 offset1:133
	ds_read2_b32 v[12:13], v12 offset0:70 offset1:135
	global_store_dwordx4 v[70:71], v[2:5], off offset:256
	s_nop 0
	s_nop 0
	s_waitcnt lgkmcnt(3)
	v_cvt_pk_bf16_f32 v2, v6, v7
	s_waitcnt lgkmcnt(2)
	v_cvt_pk_bf16_f32 v3, v8, v9
	s_waitcnt lgkmcnt(1)
	v_cvt_pk_bf16_f32 v4, v10, v11
	s_waitcnt lgkmcnt(0)
	v_cvt_pk_bf16_f32 v5, v12, v13
	global_store_dwordx4 v[70:71], v[2:5], off offset:384
	s_waitcnt vmcnt(0)
	v_mov_b32_e32 v14, v42
	v_mov_b32_e32 v15, v43
	v_mov_b32_e32 v16, v44
	v_mov_b32_e32 v17, v45
	v_mov_b64_e32 v[70:71], v[72:73]
	v_mov_b32_e32 v6, v34
	v_mov_b32_e32 v2, v38
	v_mov_b32_e32 v3, v39
	v_mov_b32_e32 v4, v40
	v_mov_b32_e32 v5, v41
	v_mov_b32_e32 v7, v35
	v_mov_b32_e32 v8, v36
	v_mov_b32_e32 v9, v37
	v_mov_b32_e32 v10, v46
	v_mov_b32_e32 v11, v47
	v_mov_b32_e32 v12, v48
	v_mov_b32_e32 v13, v49
	v_mov_b32_e32 v18, v54
	v_mov_b32_e32 v19, v55
	v_mov_b32_e32 v20, v56
	v_mov_b32_e32 v21, v57
	v_mov_b32_e32 v22, v50
	v_mov_b32_e32 v23, v51
	v_mov_b32_e32 v24, v52
	v_mov_b32_e32 v25, v53
	v_mov_b32_e32 v26, v62
	v_mov_b32_e32 v27, v63
	v_mov_b32_e32 v28, v64
	v_mov_b32_e32 v29, v65
	v_mov_b32_e32 v30, v58
	v_mov_b32_e32 v31, v59
	v_mov_b32_e32 v32, v60
	v_mov_b32_e32 v33, v61
	s_cbranch_scc0 .LBB0_1325
